# K-loop: removed mid-block setprio 0/1 flips and the redundant lgkmcnt(0) after setprio
# speedup vs baseline: 1.0086x; 1.0086x over previous
.LBB0_169:
	s_add_i32 s0, s34, 2
	s_add_u32 s1, s80, 0x80
	s_addc_u32 s35, s81, 0
	s_add_i32 s47, 0, 0x10000
	s_cmp_eq_u32 s68, s34
	s_cselect_b32 s35, s43, s35
	s_cselect_b32 s34, s42, s1
	s_cselect_b32 s67, s87, vcc_hi
	s_cselect_b32 s66, s86, vcc_lo
	s_add_i32 s1, 0, 0x14000
	s_waitcnt lgkmcnt(0)
	ds_read_b128 v[130:133], v206
	ds_read_b128 v[134:137], v206 offset:1024
	ds_read_b128 v[138:141], v206 offset:2048
	ds_read_b128 v[142:145], v206 offset:3072
	ds_read_b128 v[146:149], v207
	ds_read_b128 v[150:153], v207 offset:1024
	ds_read_b128 v[154:157], v207 offset:2048
	ds_read_b128 v[158:161], v207 offset:3072
	s_add_i32 m0, s90, 0xc000
	ds_read_b128 v[162:165], v238
	ds_read_b128 v[166:169], v238 offset:1024
	ds_read_b128 v[170:173], v238 offset:2048
	ds_read_b128 v[174:177], v238 offset:3072
	ds_read_b128 v[178:181], v238 offset:4096
	ds_read_b128 v[182:185], v238 offset:5120
	ds_read_b128 v[198:201], v238 offset:6144
	ds_read_b128 v[202:205], v238 offset:7168
	global_load_lds_dwordx4 v194, s[80:81]
	s_add_i32 m0, s90, 0xe000
	s_nop 0
	global_load_lds_dwordx4 v196, s[80:81]
	s_waitcnt vmcnt(8)
	s_waitcnt lgkmcnt(0)
	s_barrier
	s_setprio 1
	v_mfma_f32_16x16x32_bf16 v[126:129], v[130:133], v[162:165], v[126:129]
	v_mfma_f32_16x16x32_bf16 v[122:125], v[138:141], v[162:165], v[122:125]
	v_mfma_f32_16x16x32_bf16 v[118:121], v[130:133], v[170:173], v[118:121]
	v_mfma_f32_16x16x32_bf16 v[102:105], v[138:141], v[170:173], v[102:105]
	v_mfma_f32_16x16x32_bf16 v[94:97], v[130:133], v[178:181], v[94:97]
	v_mfma_f32_16x16x32_bf16 v[90:93], v[138:141], v[178:181], v[90:93]
	v_mfma_f32_16x16x32_bf16 v[78:81], v[130:133], v[198:201], v[78:81]
	v_mfma_f32_16x16x32_bf16 v[74:77], v[138:141], v[198:201], v[74:77]
	v_mfma_f32_16x16x32_bf16 v[126:129], v[134:137], v[166:169], v[126:129]
	v_mfma_f32_16x16x32_bf16 v[122:125], v[142:145], v[166:169], v[122:125]
	v_mfma_f32_16x16x32_bf16 v[118:121], v[134:137], v[174:177], v[118:121]
	v_mfma_f32_16x16x32_bf16 v[102:105], v[142:145], v[174:177], v[102:105]
	v_mfma_f32_16x16x32_bf16 v[94:97], v[134:137], v[182:185], v[94:97]
	v_mfma_f32_16x16x32_bf16 v[90:93], v[142:145], v[182:185], v[90:93]
	v_mfma_f32_16x16x32_bf16 v[78:81], v[134:137], v[202:205], v[78:81]
	v_mfma_f32_16x16x32_bf16 v[74:77], v[142:145], v[202:205], v[74:77]
	v_mfma_f32_16x16x32_bf16 v[114:117], v[146:149], v[162:165], v[114:117]
	v_mfma_f32_16x16x32_bf16 v[110:113], v[154:157], v[162:165], v[110:113]
	v_mfma_f32_16x16x32_bf16 v[106:109], v[146:149], v[170:173], v[106:109]
	v_mfma_f32_16x16x32_bf16 v[98:101], v[154:157], v[170:173], v[98:101]
	v_mfma_f32_16x16x32_bf16 v[86:89], v[146:149], v[178:181], v[86:89]
	v_mfma_f32_16x16x32_bf16 v[82:85], v[154:157], v[178:181], v[82:85]
	v_mfma_f32_16x16x32_bf16 v[70:73], v[146:149], v[198:201], v[70:73]
	v_mfma_f32_16x16x32_bf16 v[66:69], v[154:157], v[198:201], v[66:69]
	v_mfma_f32_16x16x32_bf16 v[114:117], v[150:153], v[166:169], v[114:117]
	v_mfma_f32_16x16x32_bf16 v[110:113], v[158:161], v[166:169], v[110:113]
	v_mfma_f32_16x16x32_bf16 v[106:109], v[150:153], v[174:177], v[106:109]
	v_mfma_f32_16x16x32_bf16 v[98:101], v[158:161], v[174:177], v[98:101]
	v_mfma_f32_16x16x32_bf16 v[86:89], v[150:153], v[182:185], v[86:89]
	v_mfma_f32_16x16x32_bf16 v[82:85], v[158:161], v[182:185], v[82:85]
	v_mfma_f32_16x16x32_bf16 v[70:73], v[150:153], v[202:205], v[70:73]
	v_mfma_f32_16x16x32_bf16 v[66:69], v[158:161], v[202:205], v[66:69]
	s_setprio 0
	s_barrier
	s_add_i32 s47, s47, s57
	s_mov_b32 m0, s47
	ds_read_b128 v[162:165], v238 offset:16384
	ds_read_b128 v[166:169], v238 offset:17408
	ds_read_b128 v[170:173], v238 offset:18432
	ds_read_b128 v[174:177], v238 offset:19456
	ds_read_b128 v[178:181], v238 offset:20480
	ds_read_b128 v[182:185], v238 offset:21504
	ds_read_b128 v[198:201], v238 offset:22528
	ds_read_b128 v[202:205], v238 offset:23552
	global_load_lds_dwordx4 v188, s[66:67]
	s_add_i32 m0, s47, 0x2000
	s_add_u32 s100, s66, s69
	s_addc_u32 s101, s67, 0
	s_add_i32 s1, s1, s57
	global_load_lds_dwordx4 v192, s[66:67]
	s_mov_b32 m0, s1
	s_nop 0
	global_load_lds_dwordx4 v188, s[100:101]
	s_add_i32 m0, s1, 0x2000
	s_nop 0
	global_load_lds_dwordx4 v192, s[100:101]
	s_mov_b32 m0, s90
	s_nop 0
	global_load_lds_dwordx4 v186, s[34:35]
	s_mov_b32 m0, s60
	s_nop 0
	global_load_lds_dwordx4 v190, s[34:35]
	s_waitcnt vmcnt(8)
	s_waitcnt lgkmcnt(0)
	s_barrier
	s_setprio 1
	v_mfma_f32_16x16x32_bf16 v[62:65], v[130:133], v[162:165], v[62:65]
	v_mfma_f32_16x16x32_bf16 v[58:61], v[138:141], v[162:165], v[58:61]
	v_mfma_f32_16x16x32_bf16 v[46:49], v[130:133], v[170:173], v[46:49]
	v_mfma_f32_16x16x32_bf16 v[42:45], v[138:141], v[170:173], v[42:45]
	v_mfma_f32_16x16x32_bf16 v[30:33], v[130:133], v[178:181], v[30:33]
	v_mfma_f32_16x16x32_bf16 v[26:29], v[138:141], v[178:181], v[26:29]
	v_mfma_f32_16x16x32_bf16 v[14:17], v[130:133], v[198:201], v[14:17]
	v_mfma_f32_16x16x32_bf16 v[10:13], v[138:141], v[198:201], v[10:13]
	v_mfma_f32_16x16x32_bf16 v[62:65], v[134:137], v[166:169], v[62:65]
	v_mfma_f32_16x16x32_bf16 v[58:61], v[142:145], v[166:169], v[58:61]
	v_mfma_f32_16x16x32_bf16 v[46:49], v[134:137], v[174:177], v[46:49]
	v_mfma_f32_16x16x32_bf16 v[42:45], v[142:145], v[174:177], v[42:45]
	v_mfma_f32_16x16x32_bf16 v[30:33], v[134:137], v[182:185], v[30:33]
	v_mfma_f32_16x16x32_bf16 v[26:29], v[142:145], v[182:185], v[26:29]
	v_mfma_f32_16x16x32_bf16 v[14:17], v[134:137], v[202:205], v[14:17]
	v_mfma_f32_16x16x32_bf16 v[10:13], v[142:145], v[202:205], v[10:13]
	v_mfma_f32_16x16x32_bf16 v[54:57], v[146:149], v[162:165], v[54:57]
	v_mfma_f32_16x16x32_bf16 v[50:53], v[154:157], v[162:165], v[50:53]
	v_mfma_f32_16x16x32_bf16 v[38:41], v[146:149], v[170:173], v[38:41]
	v_mfma_f32_16x16x32_bf16 v[34:37], v[154:157], v[170:173], v[34:37]
	v_mfma_f32_16x16x32_bf16 v[22:25], v[146:149], v[178:181], v[22:25]
	v_mfma_f32_16x16x32_bf16 v[18:21], v[154:157], v[178:181], v[18:21]
	v_mfma_f32_16x16x32_bf16 v[6:9], v[146:149], v[198:201], v[6:9]
	v_mfma_f32_16x16x32_bf16 v[2:5], v[154:157], v[198:201], v[2:5]
	v_mfma_f32_16x16x32_bf16 v[54:57], v[150:153], v[166:169], v[54:57]
	v_mfma_f32_16x16x32_bf16 v[50:53], v[158:161], v[166:169], v[50:53]
	v_mfma_f32_16x16x32_bf16 v[38:41], v[150:153], v[174:177], v[38:41]
	v_mfma_f32_16x16x32_bf16 v[34:37], v[158:161], v[174:177], v[34:37]
	v_mfma_f32_16x16x32_bf16 v[22:25], v[150:153], v[182:185], v[22:25]
	v_mfma_f32_16x16x32_bf16 v[18:21], v[158:161], v[182:185], v[18:21]
	v_mfma_f32_16x16x32_bf16 v[6:9], v[150:153], v[202:205], v[6:9]
	v_mfma_f32_16x16x32_bf16 v[2:5], v[158:161], v[202:205], v[2:5]
	s_setprio 0
	s_barrier
	s_add_i32 s1, 0, 0x18000
	s_add_i32 s47, 0, 0x1c000
	ds_read_b128 v[130:133], v208
	ds_read_b128 v[134:137], v208 offset:1024
	ds_read_b128 v[138:141], v208 offset:2048
	ds_read_b128 v[142:145], v208 offset:3072
	ds_read_b128 v[146:149], v209
	ds_read_b128 v[150:153], v209 offset:1024
	ds_read_b128 v[154:157], v209 offset:2048
	ds_read_b128 v[158:161], v209 offset:3072
	s_mov_b32 m0, s61
	ds_read_b128 v[162:165], v238 offset:32768
	ds_read_b128 v[166:169], v238 offset:33792
	ds_read_b128 v[170:173], v238 offset:34816
	ds_read_b128 v[174:177], v238 offset:35840
	ds_read_b128 v[178:181], v238 offset:36864
	ds_read_b128 v[182:185], v238 offset:37888
	ds_read_b128 v[198:201], v238 offset:38912
	ds_read_b128 v[202:205], v238 offset:39936
	global_load_lds_dwordx4 v194, s[34:35]
	s_mov_b32 m0, s71
	s_nop 0
	global_load_lds_dwordx4 v196, s[34:35]
	s_waitcnt vmcnt(8)
	s_waitcnt lgkmcnt(0)
	s_barrier
	s_setprio 1
	v_mfma_f32_16x16x32_bf16 v[126:129], v[130:133], v[162:165], v[126:129]
	v_mfma_f32_16x16x32_bf16 v[122:125], v[138:141], v[162:165], v[122:125]
	v_mfma_f32_16x16x32_bf16 v[118:121], v[130:133], v[170:173], v[118:121]
	v_mfma_f32_16x16x32_bf16 v[102:105], v[138:141], v[170:173], v[102:105]
	v_mfma_f32_16x16x32_bf16 v[94:97], v[130:133], v[178:181], v[94:97]
	v_mfma_f32_16x16x32_bf16 v[90:93], v[138:141], v[178:181], v[90:93]
	v_mfma_f32_16x16x32_bf16 v[78:81], v[130:133], v[198:201], v[78:81]
	v_mfma_f32_16x16x32_bf16 v[74:77], v[138:141], v[198:201], v[74:77]
	v_mfma_f32_16x16x32_bf16 v[126:129], v[134:137], v[166:169], v[126:129]
	v_mfma_f32_16x16x32_bf16 v[122:125], v[142:145], v[166:169], v[122:125]
	v_mfma_f32_16x16x32_bf16 v[118:121], v[134:137], v[174:177], v[118:121]
	v_mfma_f32_16x16x32_bf16 v[102:105], v[142:145], v[174:177], v[102:105]
	v_mfma_f32_16x16x32_bf16 v[94:97], v[134:137], v[182:185], v[94:97]
	v_mfma_f32_16x16x32_bf16 v[90:93], v[142:145], v[182:185], v[90:93]
	v_mfma_f32_16x16x32_bf16 v[78:81], v[134:137], v[202:205], v[78:81]
	v_mfma_f32_16x16x32_bf16 v[74:77], v[142:145], v[202:205], v[74:77]
	v_mfma_f32_16x16x32_bf16 v[114:117], v[146:149], v[162:165], v[114:117]
	v_mfma_f32_16x16x32_bf16 v[110:113], v[154:157], v[162:165], v[110:113]
	v_mfma_f32_16x16x32_bf16 v[106:109], v[146:149], v[170:173], v[106:109]
	v_mfma_f32_16x16x32_bf16 v[98:101], v[154:157], v[170:173], v[98:101]
	v_mfma_f32_16x16x32_bf16 v[86:89], v[146:149], v[178:181], v[86:89]
	v_mfma_f32_16x16x32_bf16 v[82:85], v[154:157], v[178:181], v[82:85]
	v_mfma_f32_16x16x32_bf16 v[70:73], v[146:149], v[198:201], v[70:73]
	v_mfma_f32_16x16x32_bf16 v[66:69], v[154:157], v[198:201], v[66:69]
	v_mfma_f32_16x16x32_bf16 v[114:117], v[150:153], v[166:169], v[114:117]
	v_mfma_f32_16x16x32_bf16 v[110:113], v[158:161], v[166:169], v[110:113]
	v_mfma_f32_16x16x32_bf16 v[106:109], v[150:153], v[174:177], v[106:109]
	v_mfma_f32_16x16x32_bf16 v[98:101], v[158:161], v[174:177], v[98:101]
	v_mfma_f32_16x16x32_bf16 v[86:89], v[150:153], v[182:185], v[86:89]
	v_mfma_f32_16x16x32_bf16 v[82:85], v[158:161], v[182:185], v[82:85]
	v_mfma_f32_16x16x32_bf16 v[70:73], v[150:153], v[202:205], v[70:73]
	v_mfma_f32_16x16x32_bf16 v[66:69], v[158:161], v[202:205], v[66:69]
	s_setprio 0
	s_barrier
	s_add_i32 s1, s1, s57
	s_add_u32 s66, s66, 0x80
	s_addc_u32 s67, s67, 0
	s_add_u32 s100, s100, 0x80
	s_addc_u32 s101, s101, 0
	s_add_u32 s34, s34, 0x80
	s_addc_u32 s35, s35, 0
	s_mov_b32 m0, s1
	ds_read_b128 v[162:165], v238 offset:49152
	ds_read_b128 v[166:169], v238 offset:50176
	ds_read_b128 v[170:173], v238 offset:51200
	ds_read_b128 v[174:177], v238 offset:52224
	ds_read_b128 v[178:181], v238 offset:53248
	ds_read_b128 v[182:185], v238 offset:54272
	ds_read_b128 v[198:201], v238 offset:55296
	ds_read_b128 v[202:205], v238 offset:56320
	global_load_lds_dwordx4 v188, s[66:67]
	s_add_i32 m0, s1, 0x2000
	s_add_i32 s1, s47, s57
	global_load_lds_dwordx4 v192, s[66:67]
	s_mov_b32 m0, s1
	s_nop 0
	global_load_lds_dwordx4 v188, s[100:101]
	s_add_i32 m0, s1, 0x2000
	s_nop 0
	global_load_lds_dwordx4 v192, s[100:101]
	s_mov_b32 m0, s64
	s_nop 0
	global_load_lds_dwordx4 v186, s[34:35]
	s_mov_b32 m0, s65
	s_nop 0
	global_load_lds_dwordx4 v190, s[34:35]
	s_waitcnt vmcnt(8)
	s_waitcnt lgkmcnt(0)
	s_barrier
	s_setprio 1
	v_mfma_f32_16x16x32_bf16 v[62:65], v[130:133], v[162:165], v[62:65]
	v_mfma_f32_16x16x32_bf16 v[58:61], v[138:141], v[162:165], v[58:61]
	v_mfma_f32_16x16x32_bf16 v[46:49], v[130:133], v[170:173], v[46:49]
	v_mfma_f32_16x16x32_bf16 v[42:45], v[138:141], v[170:173], v[42:45]
	v_mfma_f32_16x16x32_bf16 v[30:33], v[130:133], v[178:181], v[30:33]
	v_mfma_f32_16x16x32_bf16 v[26:29], v[138:141], v[178:181], v[26:29]
	v_mfma_f32_16x16x32_bf16 v[14:17], v[130:133], v[198:201], v[14:17]
	v_mfma_f32_16x16x32_bf16 v[10:13], v[138:141], v[198:201], v[10:13]
	v_mfma_f32_16x16x32_bf16 v[62:65], v[134:137], v[166:169], v[62:65]
	v_mfma_f32_16x16x32_bf16 v[58:61], v[142:145], v[166:169], v[58:61]
	v_mfma_f32_16x16x32_bf16 v[46:49], v[134:137], v[174:177], v[46:49]
	v_mfma_f32_16x16x32_bf16 v[42:45], v[142:145], v[174:177], v[42:45]
	v_mfma_f32_16x16x32_bf16 v[30:33], v[134:137], v[182:185], v[30:33]
	v_mfma_f32_16x16x32_bf16 v[26:29], v[142:145], v[182:185], v[26:29]
	v_mfma_f32_16x16x32_bf16 v[14:17], v[134:137], v[202:205], v[14:17]
	v_mfma_f32_16x16x32_bf16 v[10:13], v[142:145], v[202:205], v[10:13]
	v_mfma_f32_16x16x32_bf16 v[54:57], v[146:149], v[162:165], v[54:57]
	v_mfma_f32_16x16x32_bf16 v[50:53], v[154:157], v[162:165], v[50:53]
	v_mfma_f32_16x16x32_bf16 v[38:41], v[146:149], v[170:173], v[38:41]
	v_mfma_f32_16x16x32_bf16 v[34:37], v[154:157], v[170:173], v[34:37]
	v_mfma_f32_16x16x32_bf16 v[22:25], v[146:149], v[178:181], v[22:25]
	v_mfma_f32_16x16x32_bf16 v[18:21], v[154:157], v[178:181], v[18:21]
	v_mfma_f32_16x16x32_bf16 v[6:9], v[146:149], v[198:201], v[6:9]
	v_mfma_f32_16x16x32_bf16 v[2:5], v[154:157], v[198:201], v[2:5]
	v_mfma_f32_16x16x32_bf16 v[54:57], v[150:153], v[166:169], v[54:57]
	v_mfma_f32_16x16x32_bf16 v[50:53], v[158:161], v[166:169], v[50:53]
	v_mfma_f32_16x16x32_bf16 v[38:41], v[150:153], v[174:177], v[38:41]
	v_mfma_f32_16x16x32_bf16 v[34:37], v[158:161], v[174:177], v[34:37]
	v_mfma_f32_16x16x32_bf16 v[22:25], v[150:153], v[182:185], v[22:25]
	v_mfma_f32_16x16x32_bf16 v[18:21], v[158:161], v[182:185], v[18:21]
	v_mfma_f32_16x16x32_bf16 v[6:9], v[150:153], v[202:205], v[6:9]
	v_mfma_f32_16x16x32_bf16 v[2:5], v[158:161], v[202:205], v[2:5]
	s_setprio 0
	s_barrier
	s_add_u32 s80, s80, 0x100
	s_addc_u32 s81, s81, 0
	s_add_u32 vcc_lo, vcc_lo, 0x100
	s_addc_u32 vcc_hi, vcc_hi, 0
	s_cmp_ge_u32 s0, s91
	s_mov_b32 s34, s0
	s_cbranch_scc0 .LBB0_169
	v_readlane_b32 s0, v243, 28
	v_readlane_b32 s1, v243, 29
	s_and_b64 vcc, exec, s[0:1]
	s_cbranch_vccz .LBB0_174
	s_barrier
	v_lshl_add_u32 v198, s99, 8, v1
	s_cmp_lt_i32 s70, 1
	s_mov_b64 s[34:35], -1
	s_cbranch_scc0 .LBB0_175
